# GEMM unit entry: redundant second accumulator zero-init (about 125 of 128 v_mov per unit, 8 GEMM instances) removed
# speedup vs baseline: 1.0053x; 1.0053x over previous
;   DI bool next(int i, Unit& o) const { if (i != 0 || !valid) return false; o = u; return true; }
; #define PG8_STAGE(bufoff, gbase, voff) do { _Pragma("unroll") for (int _i = 0; _i < 2; ++_i) \
;     __builtin_amdgcn_global_load_lds((const unsigned*)((const char*)(gbase) + (voff)[_i]), (LAS unsigned*)(lds + (bufoff) + ldsw + _i * 8192), 16, 0, 0); } while (0)
; #define PG8_WAIT_V(n) asm volatile("s_waitcnt vmcnt(" #n ")" ::: "memory")
; #define PG8_BAR __builtin_amdgcn_s_barrier()
; template <class Epi, class Sched>
; DI void gemm_phase(LAS unsigned char* lds, const Gemm g, const Sched& S, const Epi& E) {
;     ...
;   f32x4 acc[2][2][4][2];
; #pragma unroll
;   for (int a = 0; a < 2; ++a)
; #pragma unroll
;     for (int b = 0; b < 2; ++b)
; #pragma unroll
;       for (int m = 0; m < 4; ++m)
; #pragma unroll
;         for (int n = 0; n < 2; ++n) acc[a][b][m][n] = (f32x4){0.f, 0.f, 0.f, 0.f};
;   bf16x8 At[4][2], B0[2][2], B1[2][2];
;   const char* cA = (const char*)g.A + (size_t)cur.pm * tstep; const char* cB = (const char*)g.Bt + (size_t)cur.pn * tstep;
;   PG8_STAGE(PG8_SB(0, 0), cB, voffB); PG8_STAGE(PG8_SA(0, 0), cA, voffA); PG8_STAGE(PG8_SB(0, 1), cB + hstepB, voffB); PG8_STAGE(PG8_SA(0, 1), cA + hstep, voffA);
;   if (wr == 1) PG8_BAR;
;   PG8_WAIT_V(4); PG8_BAR;
;   PG8_STAGE(PG8_SB(1, 0), cB + kstep, voffB); PG8_STAGE(PG8_SA(1, 0), cA + kstep, voffA); PG8_STAGE(PG8_SB(1, 1), cB + hstepB + kstep, voffB);
;   PG8_WAIT_V(6); PG8_BAR;
;   for (;;) {
;     const bool has_next = S.next(ui + 1, nxt);
;     const char* nA = has_next ? (const char*)g.A + (size_t)nxt.pm * tstep : cA; const char* nB = has_next ? (const char*)g.Bt + (size_t)nxt.pn * tstep : cB;
;     for (int t = 0; t < nt; t += 2) {
.LBB0_135:
	v_lshl_add_u64 v[4:5], s[12:13], 0, v[0:1]
	v_mov_b32_e32 v131, v1
	v_lshl_add_u64 v[6:7], s[12:13], 0, v[130:131]
	v_and_b32_e32 v132, 15, v2
	v_bfe_u32 v136, v2, 4, 2
	s_add_i32 m0, s31, 0x18000
	v_lshl_add_u64 v[2:3], v[4:5], 0, s[70:71]
	v_lshl_add_u64 v[8:9], s[14:15], 0, v[0:1]
	s_waitcnt vmcnt(4)
	s_barrier
	global_load_lds_dwordx4 v[2:3], off
	v_lshl_add_u64 v[2:3], v[6:7], 0, s[70:71]
	s_add_i32 m0, s31, 0x1a000
	s_add_i32 s37, s31, 0x8000
	v_lshl_add_u64 v[10:11], s[14:15], 0, v[130:131]
	global_load_lds_dwordx4 v[2:3], off
	v_lshl_add_u64 v[2:3], v[8:9], 0, s[70:71]
	s_mov_b32 m0, s37
	s_add_i32 s38, s31, 0xa000
	v_lshl_add_u64 v[12:13], s[18:19], 0, v[0:1]
	global_load_lds_dwordx4 v[2:3], off
	v_lshl_add_u64 v[2:3], v[10:11], 0, s[70:71]
	s_mov_b32 m0, s38
	v_lshl_add_u64 v[14:15], s[18:19], 0, v[130:131]
	global_load_lds_dwordx4 v[2:3], off
	s_add_i32 m0, s31, 0x1c000
	v_lshl_add_u64 v[2:3], v[12:13], 0, s[70:71]
	global_load_lds_dwordx4 v[2:3], off
	v_lshl_add_u64 v[2:3], v[14:15], 0, s[70:71]
	s_add_i32 m0, s31, 0x1e000
	s_lshl_b32 s18, s21, 5
	global_load_lds_dwordx4 v[2:3], off
	s_waitcnt vmcnt(6)
	s_and_b32 s27, s18, 0x60
	v_mov_b32_e32 v129, 0
	v_lshl_or_b32 v148, s20, 6, v132
	s_cmp_lt_i32 s16, 64
	v_mov_b32_e32 v128, v129
	v_mov_b32_e32 v127, v129
	v_mov_b32_e32 v126, v129
	v_mov_b32_e32 v125, v129
	v_mov_b32_e32 v124, v129
	v_mov_b32_e32 v123, v129
	v_mov_b32_e32 v122, v129
	v_mov_b32_e32 v113, v129
	v_mov_b32_e32 v112, v129
	v_mov_b32_e32 v111, v129
	v_mov_b32_e32 v110, v129
	v_mov_b32_e32 v109, v129
	v_mov_b32_e32 v108, v129
	v_mov_b32_e32 v107, v129
	v_mov_b32_e32 v106, v129
	v_mov_b32_e32 v97, v129
	v_mov_b32_e32 v96, v129
	v_mov_b32_e32 v95, v129
	v_mov_b32_e32 v94, v129
	v_mov_b32_e32 v93, v129
	v_mov_b32_e32 v92, v129
	v_mov_b32_e32 v91, v129
	v_mov_b32_e32 v90, v129
	v_mov_b32_e32 v81, v129
	v_mov_b32_e32 v80, v129
	v_mov_b32_e32 v79, v129
	v_mov_b32_e32 v78, v129
	v_mov_b32_e32 v77, v129
	v_mov_b32_e32 v76, v129
	v_mov_b32_e32 v75, v129
	v_mov_b32_e32 v74, v129
	v_mov_b32_e32 v121, v129
	v_mov_b32_e32 v120, v129
	v_mov_b32_e32 v119, v129
	v_mov_b32_e32 v118, v129
	v_mov_b32_e32 v117, v129
	v_mov_b32_e32 v116, v129
	v_mov_b32_e32 v115, v129
	v_mov_b32_e32 v114, v129
	v_mov_b32_e32 v105, v129
	v_mov_b32_e32 v104, v129
	v_mov_b32_e32 v103, v129
	v_mov_b32_e32 v102, v129
	v_mov_b32_e32 v101, v129
	v_mov_b32_e32 v100, v129
	v_mov_b32_e32 v99, v129
	v_mov_b32_e32 v98, v129
	v_mov_b32_e32 v89, v129
	v_mov_b32_e32 v88, v129
	v_mov_b32_e32 v87, v129
	v_mov_b32_e32 v86, v129
	v_mov_b32_e32 v85, v129
	v_mov_b32_e32 v84, v129
	v_mov_b32_e32 v83, v129
	v_mov_b32_e32 v82, v129
	v_mov_b32_e32 v73, v129
	v_mov_b32_e32 v72, v129
	v_mov_b32_e32 v71, v129
	v_mov_b32_e32 v70, v129
	v_mov_b32_e32 v69, v129
	v_mov_b32_e32 v68, v129
	v_mov_b32_e32 v67, v129
	v_mov_b32_e32 v66, v129
	v_mov_b32_e32 v65, v129
	v_mov_b32_e32 v64, v129
	v_mov_b32_e32 v63, v129
	v_mov_b32_e32 v62, v129
	v_mov_b32_e32 v61, v129
	v_mov_b32_e32 v60, v129
	v_mov_b32_e32 v59, v129
	v_mov_b32_e32 v58, v129
	v_mov_b32_e32 v49, v129
	v_mov_b32_e32 v48, v129
	v_mov_b32_e32 v47, v129
	v_mov_b32_e32 v46, v129
	v_mov_b32_e32 v45, v129
	v_mov_b32_e32 v44, v129
	v_mov_b32_e32 v43, v129
	v_mov_b32_e32 v42, v129
	v_mov_b32_e32 v33, v129
	v_mov_b32_e32 v32, v129
	v_mov_b32_e32 v31, v129
	v_mov_b32_e32 v30, v129
	v_mov_b32_e32 v29, v129
	v_mov_b32_e32 v28, v129
	v_mov_b32_e32 v27, v129
	v_mov_b32_e32 v26, v129
	v_mov_b32_e32 v17, v129
	v_mov_b32_e32 v16, v129
	v_mov_b32_e32 v15, v129
	v_mov_b32_e32 v14, v129
	v_mov_b32_e32 v13, v129
	v_mov_b32_e32 v12, v129
	v_mov_b32_e32 v11, v129
	v_mov_b32_e32 v10, v129
	v_mov_b32_e32 v57, v129
	v_mov_b32_e32 v56, v129
	v_mov_b32_e32 v55, v129
	v_mov_b32_e32 v54, v129
	v_mov_b32_e32 v53, v129
	v_mov_b32_e32 v52, v129
	v_mov_b32_e32 v51, v129
	v_mov_b32_e32 v50, v129
	v_mov_b32_e32 v41, v129
	v_mov_b32_e32 v40, v129
	v_mov_b32_e32 v39, v129
	v_mov_b32_e32 v38, v129
	v_mov_b32_e32 v37, v129
	v_mov_b32_e32 v36, v129
	v_mov_b32_e32 v35, v129
	v_mov_b32_e32 v34, v129
	v_mov_b32_e32 v25, v129
	v_mov_b32_e32 v24, v129
	v_mov_b32_e32 v23, v129
	v_mov_b32_e32 v22, v129
	v_mov_b32_e32 v21, v129
	v_mov_b32_e32 v20, v129
	v_mov_b32_e32 v19, v129
	v_mov_b32_e32 v18, v129
	v_mov_b32_e32 v9, v129
	v_mov_b32_e32 v8, v129
	v_mov_b32_e32 v7, v129
	v_mov_b32_e32 v6, v129
	v_mov_b32_e32 v5, v129
	v_mov_b32_e32 v4, v129
	v_mov_b32_e32 v3, v129
	v_mov_b32_e32 v2, v129
	s_barrier
	s_cbranch_scc1 .LBB0_138
	s_lshr_b32 s18, s17, 26
	s_add_i32 s18, s16, s18
	s_ashr_i32 s39, s18, 6
	v_lshlrev_b32_e32 v2, 4, v136
	v_lshlrev_b32_e32 v3, 6, v148
	s_movk_i32 s18, 0x3c0
	v_lshlrev_b32_e32 v4, 2, v148
	v_and_or_b32 v3, v3, s18, v2
	s_lshl_b32 s18, s20, 13
	v_and_b32_e32 v4, 32, v4
	v_bitop3_b32 v3, v3, s18, v4 bitop3:0xde
	v_lshlrev_b32_e32 v4, 2, v132
	v_lshl_or_b32 v2, v132, 6, v2
	s_lshl_b32 s18, s27, 7
	v_and_b32_e32 v4, 32, v4
	v_bitop3_b32 v137, v2, s18, v4 bitop3:0xde
	s_lshl_b64 s[18:19], s[0:1], 9
	s_or_b32 s1, s18, 0x100
	s_mul_i32 s17, s1, s17
	s_mul_hi_u32 s18, s1, s16
	s_add_i32 s17, s18, s17
	s_mul_i32 s18, s19, s16
	s_add_i32 s40, s39, -2
	s_add_i32 s17, s17, s18
	s_mul_i32 s1, s1, s16
	s_add_u32 s16, s60, s1
	s_addc_u32 s17, s61, s17
	v_mov_b32_e32 v2, 0
	v_lshl_add_u64 v[132:133], s[16:17], 0, v[0:1]
	v_lshl_add_u64 v[134:135], s[16:17], 0, v[130:131]
	s_mov_b32 s1, 0
	s_mov_b64 s[16:17], 0x80
	v_add_u32_e32 v138, 16, v3
	v_mov_b32_e32 v3, v2
	v_mov_b32_e32 v4, v2
	.p2align	6

;   DI bool next(int i, Unit& o) const { if (i != 0 || !valid) return false; o = u; return true; }
; #define PG8_STAGE(bufoff, gbase, voff) do { _Pragma("unroll") for (int _i = 0; _i < 2; ++_i) \
;     __builtin_amdgcn_global_load_lds((const unsigned*)((const char*)(gbase) + (voff)[_i]), (LAS unsigned*)(lds + (bufoff) + ldsw + _i * 8192), 16, 0, 0); } while (0)
; #define PG8_WAIT_V(n) asm volatile("s_waitcnt vmcnt(" #n ")" ::: "memory")
; #define PG8_BAR __builtin_amdgcn_s_barrier()
; template <class Epi, class Sched>
; DI void gemm_phase(LAS unsigned char* lds, const Gemm g, const Sched& S, const Epi& E) {
;     ...
;   f32x4 acc[2][2][4][2];
; #pragma unroll
;   for (int a = 0; a < 2; ++a)
; #pragma unroll
;     for (int b = 0; b < 2; ++b)
; #pragma unroll
;       for (int m = 0; m < 4; ++m)
; #pragma unroll
;         for (int n = 0; n < 2; ++n) acc[a][b][m][n] = (f32x4){0.f, 0.f, 0.f, 0.f};
;   bf16x8 At[4][2], B0[2][2], B1[2][2];
;   const char* cA = (const char*)g.A + (size_t)cur.pm * tstep; const char* cB = (const char*)g.Bt + (size_t)cur.pn * tstep;
;   PG8_STAGE(PG8_SB(0, 0), cB, voffB); PG8_STAGE(PG8_SA(0, 0), cA, voffA); PG8_STAGE(PG8_SB(0, 1), cB + hstepB, voffB); PG8_STAGE(PG8_SA(0, 1), cA + hstep, voffA);
;   if (wr == 1) PG8_BAR;
;   PG8_WAIT_V(4); PG8_BAR;
;   PG8_STAGE(PG8_SB(1, 0), cB + kstep, voffB); PG8_STAGE(PG8_SA(1, 0), cA + kstep, voffA); PG8_STAGE(PG8_SB(1, 1), cB + hstepB + kstep, voffB);
;   PG8_WAIT_V(6); PG8_BAR;
;   for (;;) {
;     const bool has_next = S.next(ui + 1, nxt);
;     const char* nA = has_next ? (const char*)g.A + (size_t)nxt.pm * tstep : cA; const char* nB = has_next ? (const char*)g.Bt + (size_t)nxt.pn * tstep : cB;
;     for (int t = 0; t < nt; t += 2) {
.LBB0_151:
	v_lshl_add_u64 v[4:5], s[2:3], 0, v[0:1]
	v_mov_b32_e32 v131, v1
	v_lshl_add_u64 v[6:7], s[2:3], 0, v[130:131]
	v_and_b32_e32 v132, 15, v2
	v_bfe_u32 v136, v2, 4, 2
	s_add_i32 m0, s24, 0x18000
	v_lshl_add_u64 v[2:3], v[4:5], 0, s[70:71]
	v_lshl_add_u64 v[8:9], s[12:13], 0, v[0:1]
	s_waitcnt vmcnt(4)
	s_barrier
	global_load_lds_dwordx4 v[2:3], off
	v_lshl_add_u64 v[2:3], v[6:7], 0, s[70:71]
	s_add_i32 m0, s24, 0x1a000
	s_add_i32 s30, s24, 0x8000
	v_lshl_add_u64 v[10:11], s[12:13], 0, v[130:131]
	global_load_lds_dwordx4 v[2:3], off
	v_lshl_add_u64 v[2:3], v[8:9], 0, s[70:71]
	s_mov_b32 m0, s30
	s_add_i32 s31, s24, 0xa000
	v_lshl_add_u64 v[12:13], s[16:17], 0, v[0:1]
	global_load_lds_dwordx4 v[2:3], off
	v_lshl_add_u64 v[2:3], v[10:11], 0, s[70:71]
	s_mov_b32 m0, s31
	v_lshl_add_u64 v[14:15], s[16:17], 0, v[130:131]
	global_load_lds_dwordx4 v[2:3], off
	s_add_i32 m0, s24, 0x1c000
	v_lshl_add_u64 v[2:3], v[12:13], 0, s[70:71]
	global_load_lds_dwordx4 v[2:3], off
	v_lshl_add_u64 v[2:3], v[14:15], 0, s[70:71]
	s_add_i32 m0, s24, 0x1e000
	s_lshl_b32 s16, s19, 5
	global_load_lds_dwordx4 v[2:3], off
	s_waitcnt vmcnt(6)
	s_and_b32 s22, s16, 0x60
	v_mov_b32_e32 v129, 0
	v_lshl_or_b32 v148, s18, 6, v132
	s_cmp_lt_i32 s14, 64
	v_mov_b32_e32 v128, v129
	v_mov_b32_e32 v127, v129
	v_mov_b32_e32 v126, v129
	v_mov_b32_e32 v125, v129
	v_mov_b32_e32 v124, v129
	v_mov_b32_e32 v123, v129
	v_mov_b32_e32 v122, v129
	v_mov_b32_e32 v113, v129
	v_mov_b32_e32 v112, v129
	v_mov_b32_e32 v111, v129
	v_mov_b32_e32 v110, v129
	v_mov_b32_e32 v109, v129
	v_mov_b32_e32 v108, v129
	v_mov_b32_e32 v107, v129
	v_mov_b32_e32 v106, v129
	v_mov_b32_e32 v97, v129
	v_mov_b32_e32 v96, v129
	v_mov_b32_e32 v95, v129
	v_mov_b32_e32 v94, v129
	v_mov_b32_e32 v93, v129
	v_mov_b32_e32 v92, v129
	v_mov_b32_e32 v91, v129
	v_mov_b32_e32 v90, v129
	v_mov_b32_e32 v81, v129
	v_mov_b32_e32 v80, v129
	v_mov_b32_e32 v79, v129
	v_mov_b32_e32 v78, v129
	v_mov_b32_e32 v77, v129
	v_mov_b32_e32 v76, v129
	v_mov_b32_e32 v75, v129
	v_mov_b32_e32 v74, v129
	v_mov_b32_e32 v121, v129
	v_mov_b32_e32 v120, v129
	v_mov_b32_e32 v119, v129
	v_mov_b32_e32 v118, v129
	v_mov_b32_e32 v117, v129
	v_mov_b32_e32 v116, v129
	v_mov_b32_e32 v115, v129
	v_mov_b32_e32 v114, v129
	v_mov_b32_e32 v105, v129
	v_mov_b32_e32 v104, v129
	v_mov_b32_e32 v103, v129
	v_mov_b32_e32 v102, v129
	v_mov_b32_e32 v101, v129
	v_mov_b32_e32 v100, v129
	v_mov_b32_e32 v99, v129
	v_mov_b32_e32 v98, v129
	v_mov_b32_e32 v89, v129
	v_mov_b32_e32 v88, v129
	v_mov_b32_e32 v87, v129
	v_mov_b32_e32 v86, v129
	v_mov_b32_e32 v85, v129
	v_mov_b32_e32 v84, v129
	v_mov_b32_e32 v83, v129
	v_mov_b32_e32 v82, v129
	v_mov_b32_e32 v73, v129
	v_mov_b32_e32 v72, v129
	v_mov_b32_e32 v71, v129
	v_mov_b32_e32 v70, v129
	v_mov_b32_e32 v69, v129
	v_mov_b32_e32 v68, v129
	v_mov_b32_e32 v67, v129
	v_mov_b32_e32 v66, v129
	v_mov_b32_e32 v65, v129
	v_mov_b32_e32 v64, v129
	v_mov_b32_e32 v63, v129
	v_mov_b32_e32 v62, v129
	v_mov_b32_e32 v61, v129
	v_mov_b32_e32 v60, v129
	v_mov_b32_e32 v59, v129
	v_mov_b32_e32 v58, v129
	v_mov_b32_e32 v49, v129
	v_mov_b32_e32 v48, v129
	v_mov_b32_e32 v47, v129
	v_mov_b32_e32 v46, v129
	v_mov_b32_e32 v45, v129
	v_mov_b32_e32 v44, v129
	v_mov_b32_e32 v43, v129
	v_mov_b32_e32 v42, v129
	v_mov_b32_e32 v33, v129
	v_mov_b32_e32 v32, v129
	v_mov_b32_e32 v31, v129
	v_mov_b32_e32 v30, v129
	v_mov_b32_e32 v29, v129
	v_mov_b32_e32 v28, v129
	v_mov_b32_e32 v27, v129
	v_mov_b32_e32 v26, v129
	v_mov_b32_e32 v17, v129
	v_mov_b32_e32 v16, v129
	v_mov_b32_e32 v15, v129
	v_mov_b32_e32 v14, v129
	v_mov_b32_e32 v13, v129
	v_mov_b32_e32 v12, v129
	v_mov_b32_e32 v11, v129
	v_mov_b32_e32 v10, v129
	v_mov_b32_e32 v57, v129
	v_mov_b32_e32 v56, v129
	v_mov_b32_e32 v55, v129
	v_mov_b32_e32 v54, v129
	v_mov_b32_e32 v53, v129
	v_mov_b32_e32 v52, v129
	v_mov_b32_e32 v51, v129
	v_mov_b32_e32 v50, v129
	v_mov_b32_e32 v41, v129
	v_mov_b32_e32 v40, v129
	v_mov_b32_e32 v39, v129
	v_mov_b32_e32 v38, v129
	v_mov_b32_e32 v37, v129
	v_mov_b32_e32 v36, v129
	v_mov_b32_e32 v35, v129
	v_mov_b32_e32 v34, v129
	v_mov_b32_e32 v25, v129
	v_mov_b32_e32 v24, v129
	v_mov_b32_e32 v23, v129
	v_mov_b32_e32 v22, v129
	v_mov_b32_e32 v21, v129
	v_mov_b32_e32 v20, v129
	v_mov_b32_e32 v19, v129
	v_mov_b32_e32 v18, v129
	v_mov_b32_e32 v9, v129
	v_mov_b32_e32 v8, v129
	v_mov_b32_e32 v7, v129
	v_mov_b32_e32 v6, v129
	v_mov_b32_e32 v5, v129
	v_mov_b32_e32 v4, v129
	v_mov_b32_e32 v3, v129
	v_mov_b32_e32 v2, v129
	s_barrier
	s_cbranch_scc1 .LBB0_154
	s_lshr_b32 s15, s15, 26
	s_add_i32 s15, s14, s15
	s_ashr_i32 s34, s15, 6
	v_lshlrev_b32_e32 v2, 4, v136
	v_lshlrev_b32_e32 v3, 6, v148
	s_movk_i32 s15, 0x3c0
	v_lshlrev_b32_e32 v4, 2, v148
	v_and_or_b32 v3, v3, s15, v2
	s_lshl_b32 s15, s18, 13
	v_and_b32_e32 v4, 32, v4
	v_bitop3_b32 v3, v3, s15, v4 bitop3:0xde
	v_lshlrev_b32_e32 v4, 2, v132
	v_lshl_or_b32 v2, v132, 6, v2
	s_lshl_b32 s15, s22, 7
	v_and_b32_e32 v4, 32, v4
	v_readlane_b32 s16, v253, 33
	s_add_i32 s35, s34, -2
	v_bitop3_b32 v137, v2, s15, v4 bitop3:0xde
	s_mul_hi_i32 s15, s16, s14
	s_mul_i32 s14, s16, s14
	s_add_u32 s14, s60, s14
	s_addc_u32 s15, s61, s15
	v_mov_b32_e32 v2, 0
	v_lshl_add_u64 v[132:133], s[14:15], 0, v[0:1]
	v_lshl_add_u64 v[134:135], s[14:15], 0, v[130:131]
	s_mov_b32 s16, 0
	s_mov_b64 s[14:15], 0x5800080
	v_add_u32_e32 v138, 16, v3
	v_mov_b32_e32 v3, v2
	v_mov_b32_e32 v4, v2
	.p2align	6

; template <class Epi, class Sched>
; DI void gemm_phase(LAS unsigned char* lds, const Gemm g, const Sched& S, const Epi& E) {
;     ...
;     if (!has_next) break;
; #pragma unroll
;     for (int a = 0; a < 2; ++a)
; #pragma unroll
;       for (int b = 0; b < 2; ++b)
; #pragma unroll
;         for (int m = 0; m < 4; ++m)
; #pragma unroll
;           for (int n = 0; n < 2; ++n) acc[a][b][m][n] = (f32x4){0.f, 0.f, 0.f, 0.f};
;     cur = nxt; cA = nA; cB = nB; ++ui;
.LBB0_176:
	s_waitcnt vmcnt(8)
	v_mov_b32_e32 v125, 0
	s_andn2_b64 vcc, exec, s[16:17]
	v_mov_b32_e32 v124, v125
	v_mov_b32_e32 v123, v125
	v_mov_b32_e32 v122, v125
	v_mov_b32_e32 v121, v125
	v_mov_b32_e32 v120, v125
	v_mov_b32_e32 v119, v125
	v_mov_b32_e32 v118, v125
	v_mov_b32_e32 v113, v125
	v_mov_b32_e32 v112, v125
	v_mov_b32_e32 v111, v125
	v_mov_b32_e32 v110, v125
	v_mov_b32_e32 v105, v125
	v_mov_b32_e32 v104, v125
	v_mov_b32_e32 v103, v125
	v_mov_b32_e32 v102, v125
	v_mov_b32_e32 v97, v125
	v_mov_b32_e32 v96, v125
	v_mov_b32_e32 v95, v125
	v_mov_b32_e32 v94, v125
	v_mov_b32_e32 v89, v125
	v_mov_b32_e32 v88, v125
	v_mov_b32_e32 v87, v125
	v_mov_b32_e32 v86, v125
	v_mov_b32_e32 v81, v125
	v_mov_b32_e32 v80, v125
	v_mov_b32_e32 v79, v125
	v_mov_b32_e32 v78, v125
	v_mov_b32_e32 v73, v125
	v_mov_b32_e32 v72, v125
	v_mov_b32_e32 v71, v125
	v_mov_b32_e32 v70, v125
	v_mov_b32_e32 v129, v125
	v_mov_b32_e32 v128, v125
	v_mov_b32_e32 v127, v125
	v_mov_b32_e32 v126, v125
	v_mov_b32_e32 v117, v125
	v_mov_b32_e32 v116, v125
	v_mov_b32_e32 v115, v125
	v_mov_b32_e32 v114, v125
	v_mov_b32_e32 v109, v125
	v_mov_b32_e32 v108, v125
	v_mov_b32_e32 v107, v125
	v_mov_b32_e32 v106, v125
	v_mov_b32_e32 v101, v125
	v_mov_b32_e32 v100, v125
	v_mov_b32_e32 v99, v125
	v_mov_b32_e32 v98, v125
	v_mov_b32_e32 v93, v125
	v_mov_b32_e32 v92, v125
	v_mov_b32_e32 v91, v125
	v_mov_b32_e32 v90, v125
	v_mov_b32_e32 v85, v125
	v_mov_b32_e32 v84, v125
	v_mov_b32_e32 v83, v125
	v_mov_b32_e32 v82, v125
	v_mov_b32_e32 v77, v125
	v_mov_b32_e32 v76, v125
	v_mov_b32_e32 v75, v125
	v_mov_b32_e32 v74, v125
	v_mov_b32_e32 v69, v125
	v_mov_b32_e32 v68, v125
	v_mov_b32_e32 v67, v125
	v_mov_b32_e32 v66, v125
	v_mov_b32_e32 v65, v125
	v_mov_b32_e32 v64, v125
	v_mov_b32_e32 v63, v125
	v_mov_b32_e32 v62, v125
	v_mov_b32_e32 v57, v125
	v_mov_b32_e32 v56, v125
	v_mov_b32_e32 v55, v125
	v_mov_b32_e32 v54, v125
	v_mov_b32_e32 v49, v125
	v_mov_b32_e32 v48, v125
	v_mov_b32_e32 v47, v125
	v_mov_b32_e32 v46, v125
	v_mov_b32_e32 v41, v125
	v_mov_b32_e32 v40, v125
	v_mov_b32_e32 v39, v125
	v_mov_b32_e32 v38, v125
	v_mov_b32_e32 v33, v125
	v_mov_b32_e32 v32, v125
	v_mov_b32_e32 v31, v125
	v_mov_b32_e32 v30, v125
	v_mov_b32_e32 v25, v125
	v_mov_b32_e32 v24, v125
	v_mov_b32_e32 v23, v125
	v_mov_b32_e32 v22, v125
	v_mov_b32_e32 v17, v125
	v_mov_b32_e32 v16, v125
	v_mov_b32_e32 v15, v125
	v_mov_b32_e32 v14, v125
	v_mov_b32_e32 v9, v125
	v_mov_b32_e32 v8, v125
	v_mov_b32_e32 v7, v125
	v_mov_b32_e32 v6, v125
	v_mov_b32_e32 v61, v125
	v_mov_b32_e32 v60, v125
	v_mov_b32_e32 v59, v125
	v_mov_b32_e32 v58, v125
	v_mov_b32_e32 v53, v125
	v_mov_b32_e32 v52, v125
	v_mov_b32_e32 v51, v125
	v_mov_b32_e32 v50, v125
	v_mov_b32_e32 v45, v125
	v_mov_b32_e32 v44, v125
	v_mov_b32_e32 v43, v125
	v_mov_b32_e32 v42, v125
	v_mov_b32_e32 v37, v125
	v_mov_b32_e32 v36, v125
	v_mov_b32_e32 v35, v125
	v_mov_b32_e32 v34, v125
	v_mov_b32_e32 v29, v125
	v_mov_b32_e32 v28, v125
	v_mov_b32_e32 v27, v125
	v_mov_b32_e32 v26, v125
	v_mov_b32_e32 v21, v125
	v_mov_b32_e32 v20, v125
	v_mov_b32_e32 v19, v125
	v_mov_b32_e32 v18, v125
	v_mov_b32_e32 v13, v125
	v_mov_b32_e32 v12, v125
	v_mov_b32_e32 v11, v125
	v_mov_b32_e32 v10, v125
	v_mov_b32_e32 v5, v125
	v_mov_b32_e32 v4, v125
	v_mov_b32_e32 v3, v125
	v_mov_b32_e32 v2, v125
	s_cbranch_vccnz .LBB0_162
	s_add_u32 s22, s22, 0x80
	s_addc_u32 s23, s23, 0
	s_add_u32 s49, s24, 0x100
	s_addc_u32 s50, s25, 0
	s_mov_b32 s24, 0
	.p2align	6

;   DI bool next(int i, Unit& o) const { if (i != 0 || !valid) return false; o = u; return true; }
; #define PG8_STAGE(bufoff, gbase, voff) do { _Pragma("unroll") for (int _i = 0; _i < 2; ++_i) \
;     __builtin_amdgcn_global_load_lds((const unsigned*)((const char*)(gbase) + (voff)[_i]), (LAS unsigned*)(lds + (bufoff) + ldsw + _i * 8192), 16, 0, 0); } while (0)
; #define PG8_WAIT_V(n) asm volatile("s_waitcnt vmcnt(" #n ")" ::: "memory")
; #define PG8_BAR __builtin_amdgcn_s_barrier()
; template <class Epi, class Sched>
; DI void gemm_phase(LAS unsigned char* lds, const Gemm g, const Sched& S, const Epi& E) {
;     ...
;   f32x4 acc[2][2][4][2];
; #pragma unroll
;   for (int a = 0; a < 2; ++a)
; #pragma unroll
;     for (int b = 0; b < 2; ++b)
; #pragma unroll
;       for (int m = 0; m < 4; ++m)
; #pragma unroll
;         for (int n = 0; n < 2; ++n) acc[a][b][m][n] = (f32x4){0.f, 0.f, 0.f, 0.f};
;   bf16x8 At[4][2], B0[2][2], B1[2][2];
;   const char* cA = (const char*)g.A + (size_t)cur.pm * tstep; const char* cB = (const char*)g.Bt + (size_t)cur.pn * tstep;
;   PG8_STAGE(PG8_SB(0, 0), cB, voffB); PG8_STAGE(PG8_SA(0, 0), cA, voffA); PG8_STAGE(PG8_SB(0, 1), cB + hstepB, voffB); PG8_STAGE(PG8_SA(0, 1), cA + hstep, voffA);
;   if (wr == 1) PG8_BAR;
;   PG8_WAIT_V(4); PG8_BAR;
;   PG8_STAGE(PG8_SB(1, 0), cB + kstep, voffB); PG8_STAGE(PG8_SA(1, 0), cA + kstep, voffA); PG8_STAGE(PG8_SB(1, 1), cB + hstepB + kstep, voffB);
;   PG8_WAIT_V(6); PG8_BAR;
;   for (;;) {
;     const bool has_next = S.next(ui + 1, nxt);
;     const char* nA = has_next ? (const char*)g.A + (size_t)nxt.pm * tstep : cA; const char* nB = has_next ? (const char*)g.Bt + (size_t)nxt.pn * tstep : cB;
;     for (int t = 0; t < nt; t += 2) {
.LBB0_189:
	v_lshl_add_u64 v[4:5], s[2:3], 0, v[0:1]
	v_mov_b32_e32 v131, v1
	v_and_b32_e32 v142, 15, v2
	v_lshrrev_b32_e32 v2, 1, v2
	v_lshl_add_u64 v[6:7], s[2:3], 0, v[130:131]
	v_mov_b32_e32 v135, v1
	v_and_b32_e32 v140, 24, v2
	s_add_i32 m0, s23, 0x18000
	v_lshl_add_u64 v[2:3], v[4:5], 0, s[70:71]
	v_lshl_add_u64 v[8:9], s[12:13], 0, v[134:135]
	v_mov_b32_e32 v133, v1
	s_waitcnt vmcnt(4)
	s_barrier
	global_load_lds_dwordx4 v[2:3], off
	v_lshl_add_u64 v[2:3], v[6:7], 0, s[70:71]
	s_add_i32 m0, s23, 0x1a000
	s_add_i32 s27, s23, 0x8000
	v_lshl_add_u64 v[10:11], s[12:13], 0, v[132:133]
	global_load_lds_dwordx4 v[2:3], off
	v_lshl_add_u64 v[2:3], v[8:9], 0, s[70:71]
	s_mov_b32 m0, s27
	s_add_i32 s29, s23, 0xa000
	v_lshl_add_u64 v[12:13], s[16:17], 0, v[0:1]
	global_load_lds_dwordx4 v[2:3], off
	v_lshl_add_u64 v[2:3], v[10:11], 0, s[70:71]
	s_mov_b32 m0, s29
	v_lshl_add_u64 v[14:15], s[16:17], 0, v[130:131]
	global_load_lds_dwordx4 v[2:3], off
	s_add_i32 m0, s23, 0x1c000
	v_lshl_add_u64 v[2:3], v[12:13], 0, s[70:71]
	global_load_lds_dwordx4 v[2:3], off
	v_lshl_add_u64 v[2:3], v[14:15], 0, s[70:71]
	s_add_i32 m0, s23, 0x1e000
	s_lshl_b32 s16, s19, 5
	global_load_lds_dwordx4 v[2:3], off
	s_waitcnt vmcnt(6)
	s_and_b32 s21, s16, 0x60
	v_mov_b32_e32 v129, 0
	v_lshl_or_b32 v141, s18, 6, v142
	s_cmp_lt_i32 s14, 64
	v_mov_b32_e32 v128, v129
	v_mov_b32_e32 v127, v129
	v_mov_b32_e32 v126, v129
	v_mov_b32_e32 v121, v129
	v_mov_b32_e32 v120, v129
	v_mov_b32_e32 v119, v129
	v_mov_b32_e32 v118, v129
	v_mov_b32_e32 v113, v129
	v_mov_b32_e32 v112, v129
	v_mov_b32_e32 v111, v129
	v_mov_b32_e32 v110, v129
	v_mov_b32_e32 v105, v129
	v_mov_b32_e32 v104, v129
	v_mov_b32_e32 v103, v129
	v_mov_b32_e32 v102, v129
	v_mov_b32_e32 v97, v129
	v_mov_b32_e32 v96, v129
	v_mov_b32_e32 v95, v129
	v_mov_b32_e32 v94, v129
	v_mov_b32_e32 v89, v129
	v_mov_b32_e32 v88, v129
	v_mov_b32_e32 v87, v129
	v_mov_b32_e32 v86, v129
	v_mov_b32_e32 v81, v129
	v_mov_b32_e32 v80, v129
	v_mov_b32_e32 v79, v129
	v_mov_b32_e32 v78, v129
	v_mov_b32_e32 v73, v129
	v_mov_b32_e32 v72, v129
	v_mov_b32_e32 v71, v129
	v_mov_b32_e32 v70, v129
	v_mov_b32_e32 v125, v129
	v_mov_b32_e32 v124, v129
	v_mov_b32_e32 v123, v129
	v_mov_b32_e32 v122, v129
	v_mov_b32_e32 v117, v129
	v_mov_b32_e32 v116, v129
	v_mov_b32_e32 v115, v129
	v_mov_b32_e32 v114, v129
	v_mov_b32_e32 v109, v129
	v_mov_b32_e32 v108, v129
	v_mov_b32_e32 v107, v129
	v_mov_b32_e32 v106, v129
	v_mov_b32_e32 v101, v129
	v_mov_b32_e32 v100, v129
	v_mov_b32_e32 v99, v129
	v_mov_b32_e32 v98, v129
	v_mov_b32_e32 v93, v129
	v_mov_b32_e32 v92, v129
	v_mov_b32_e32 v91, v129
	v_mov_b32_e32 v90, v129
	v_mov_b32_e32 v85, v129
	v_mov_b32_e32 v84, v129
	v_mov_b32_e32 v83, v129
	v_mov_b32_e32 v82, v129
	v_mov_b32_e32 v77, v129
	v_mov_b32_e32 v76, v129
	v_mov_b32_e32 v75, v129
	v_mov_b32_e32 v74, v129
	v_mov_b32_e32 v69, v129
	v_mov_b32_e32 v68, v129
	v_mov_b32_e32 v67, v129
	v_mov_b32_e32 v66, v129
	v_mov_b32_e32 v65, v129
	v_mov_b32_e32 v64, v129
	v_mov_b32_e32 v63, v129
	v_mov_b32_e32 v62, v129
	v_mov_b32_e32 v57, v129
	v_mov_b32_e32 v56, v129
	v_mov_b32_e32 v55, v129
	v_mov_b32_e32 v54, v129
	v_mov_b32_e32 v49, v129
	v_mov_b32_e32 v48, v129
	v_mov_b32_e32 v47, v129
	v_mov_b32_e32 v46, v129
	v_mov_b32_e32 v41, v129
	v_mov_b32_e32 v40, v129
	v_mov_b32_e32 v39, v129
	v_mov_b32_e32 v38, v129
	v_mov_b32_e32 v33, v129
	v_mov_b32_e32 v32, v129
	v_mov_b32_e32 v31, v129
	v_mov_b32_e32 v30, v129
	v_mov_b32_e32 v25, v129
	v_mov_b32_e32 v24, v129
	v_mov_b32_e32 v23, v129
	v_mov_b32_e32 v22, v129
	v_mov_b32_e32 v17, v129
	v_mov_b32_e32 v16, v129
	v_mov_b32_e32 v15, v129
	v_mov_b32_e32 v14, v129
	v_mov_b32_e32 v9, v129
	v_mov_b32_e32 v8, v129
	v_mov_b32_e32 v7, v129
	v_mov_b32_e32 v6, v129
	v_mov_b32_e32 v61, v129
	v_mov_b32_e32 v60, v129
	v_mov_b32_e32 v59, v129
	v_mov_b32_e32 v58, v129
	v_mov_b32_e32 v53, v129
	v_mov_b32_e32 v52, v129
	v_mov_b32_e32 v51, v129
	v_mov_b32_e32 v50, v129
	v_mov_b32_e32 v45, v129
	v_mov_b32_e32 v44, v129
	v_mov_b32_e32 v43, v129
	v_mov_b32_e32 v42, v129
	v_mov_b32_e32 v37, v129
	v_mov_b32_e32 v36, v129
	v_mov_b32_e32 v35, v129
	v_mov_b32_e32 v34, v129
	v_mov_b32_e32 v29, v129
	v_mov_b32_e32 v28, v129
	v_mov_b32_e32 v27, v129
	v_mov_b32_e32 v26, v129
	v_mov_b32_e32 v21, v129
	v_mov_b32_e32 v20, v129
	v_mov_b32_e32 v19, v129
	v_mov_b32_e32 v18, v129
	v_mov_b32_e32 v13, v129
	v_mov_b32_e32 v12, v129
	v_mov_b32_e32 v11, v129
	v_mov_b32_e32 v10, v129
	v_mov_b32_e32 v5, v129
	v_mov_b32_e32 v4, v129
	v_mov_b32_e32 v3, v129
	v_mov_b32_e32 v2, v129
	s_barrier
	s_cbranch_scc1 .LBB0_192
	s_lshr_b32 s15, s15, 26
	s_add_i32 s15, s14, s15
	s_ashr_i32 s30, s15, 6
	v_lshlrev_b32_e32 v2, 6, v141
	v_lshlrev_b32_e32 v3, 1, v140
	s_movk_i32 s15, 0x3c0
	v_lshlrev_b32_e32 v4, 2, v141
	v_and_or_b32 v2, v2, s15, v3
	s_lshl_b32 s15, s18, 13
	v_and_b32_e32 v4, 32, v4
	v_bitop3_b32 v4, v2, s15, v4 bitop3:0xde
	v_lshl_or_b32 v2, v142, 6, v3
	v_lshlrev_b32_e32 v3, 2, v142
	s_lshl_b32 s15, s21, 7
	v_and_b32_e32 v3, 32, v3
	v_readlane_b32 s16, v253, 35
	s_add_i32 s31, s30, -2
	v_bitop3_b32 v142, v2, s15, v3 bitop3:0xde
	s_mul_hi_i32 s15, s16, s14
	s_mul_i32 s14, s16, s14
	v_add_u32_e32 v2, v144, v136
	s_add_u32 s14, s86, s14
	v_add_lshl_u32 v2, v2, v137, 1
	v_mov_b32_e32 v3, v1
	s_addc_u32 s15, s87, s15
	v_lshl_add_u64 v[136:137], s[14:15], 0, v[2:3]
	v_add_u32_e32 v2, v143, v138
	v_add_lshl_u32 v2, v2, v139, 1
	v_lshl_add_u64 v[138:139], s[14:15], 0, v[2:3]
	v_mov_b32_e32 v2, 0
	s_mov_b32 s16, 0
	s_mov_b64 s[14:15], 0x2000080
	v_add_u32_e32 v143, 16, v4
	v_mov_b32_e32 v3, v2
	v_mov_b32_e32 v4, v2
	.p2align	6

;   DI bool next(int i, Unit& o) const { if (i != 0 || !valid) return false; o = u; return true; }
; #define PG8_STAGE(bufoff, gbase, voff) do { _Pragma("unroll") for (int _i = 0; _i < 2; ++_i) \
;     __builtin_amdgcn_global_load_lds((const unsigned*)((const char*)(gbase) + (voff)[_i]), (LAS unsigned*)(lds + (bufoff) + ldsw + _i * 8192), 16, 0, 0); } while (0)
; #define PG8_WAIT_V(n) asm volatile("s_waitcnt vmcnt(" #n ")" ::: "memory")
; #define PG8_BAR __builtin_amdgcn_s_barrier()
; template <class Epi, class Sched>
; DI void gemm_phase(LAS unsigned char* lds, const Gemm g, const Sched& S, const Epi& E) {
;     ...
;   f32x4 acc[2][2][4][2];
; #pragma unroll
;   for (int a = 0; a < 2; ++a)
; #pragma unroll
;     for (int b = 0; b < 2; ++b)
; #pragma unroll
;       for (int m = 0; m < 4; ++m)
; #pragma unroll
;         for (int n = 0; n < 2; ++n) acc[a][b][m][n] = (f32x4){0.f, 0.f, 0.f, 0.f};
;   bf16x8 At[4][2], B0[2][2], B1[2][2];
;   const char* cA = (const char*)g.A + (size_t)cur.pm * tstep; const char* cB = (const char*)g.Bt + (size_t)cur.pn * tstep;
;   PG8_STAGE(PG8_SB(0, 0), cB, voffB); PG8_STAGE(PG8_SA(0, 0), cA, voffA); PG8_STAGE(PG8_SB(0, 1), cB + hstepB, voffB); PG8_STAGE(PG8_SA(0, 1), cA + hstep, voffA);
;   if (wr == 1) PG8_BAR;
;   PG8_WAIT_V(4); PG8_BAR;
;   PG8_STAGE(PG8_SB(1, 0), cB + kstep, voffB); PG8_STAGE(PG8_SA(1, 0), cA + kstep, voffA); PG8_STAGE(PG8_SB(1, 1), cB + hstepB + kstep, voffB);
;   PG8_WAIT_V(6); PG8_BAR;
;   for (;;) {
;     const bool has_next = S.next(ui + 1, nxt);
;     const char* nA = has_next ? (const char*)g.A + (size_t)nxt.pm * tstep : cA; const char* nB = has_next ? (const char*)g.Bt + (size_t)nxt.pn * tstep : cB;
;     for (int t = 0; t < nt; t += 2) {
.LBB0_215:
	v_lshl_add_u64 v[4:5], s[12:13], 0, v[0:1]
	v_mov_b32_e32 v131, v1
	v_lshl_add_u64 v[6:7], s[12:13], 0, v[130:131]
	v_and_b32_e32 v132, 15, v2
	v_bfe_u32 v136, v2, 4, 2
	s_add_i32 m0, s30, 0x18000
	v_lshl_add_u64 v[2:3], v[4:5], 0, s[70:71]
	v_lshl_add_u64 v[8:9], s[14:15], 0, v[0:1]
	s_waitcnt vmcnt(4)
	s_barrier
	global_load_lds_dwordx4 v[2:3], off
	v_lshl_add_u64 v[2:3], v[6:7], 0, s[70:71]
	s_add_i32 m0, s30, 0x1a000
	s_add_i32 s36, s30, 0x8000
	v_lshl_add_u64 v[10:11], s[14:15], 0, v[130:131]
	global_load_lds_dwordx4 v[2:3], off
	v_lshl_add_u64 v[2:3], v[8:9], 0, s[70:71]
	s_mov_b32 m0, s36
	s_add_i32 s37, s30, 0xa000
	v_lshl_add_u64 v[12:13], s[18:19], 0, v[0:1]
	global_load_lds_dwordx4 v[2:3], off
	v_lshl_add_u64 v[2:3], v[10:11], 0, s[70:71]
	s_mov_b32 m0, s37
	v_lshl_add_u64 v[14:15], s[18:19], 0, v[130:131]
	global_load_lds_dwordx4 v[2:3], off
	s_add_i32 m0, s30, 0x1c000
	v_lshl_add_u64 v[2:3], v[12:13], 0, s[70:71]
	global_load_lds_dwordx4 v[2:3], off
	v_lshl_add_u64 v[2:3], v[14:15], 0, s[70:71]
	s_add_i32 m0, s30, 0x1e000
	s_lshl_b32 s18, s21, 5
	global_load_lds_dwordx4 v[2:3], off
	s_waitcnt vmcnt(6)
	s_and_b32 s27, s18, 0x60
	v_mov_b32_e32 v129, 0
	v_lshl_or_b32 v146, s20, 6, v132
	s_cmp_lt_i32 s16, 64
	v_mov_b32_e32 v128, v129
	v_mov_b32_e32 v127, v129
	v_mov_b32_e32 v126, v129
	v_mov_b32_e32 v125, v129
	v_mov_b32_e32 v124, v129
	v_mov_b32_e32 v123, v129
	v_mov_b32_e32 v122, v129
	v_mov_b32_e32 v113, v129
	v_mov_b32_e32 v112, v129
	v_mov_b32_e32 v111, v129
	v_mov_b32_e32 v110, v129
	v_mov_b32_e32 v109, v129
	v_mov_b32_e32 v108, v129
	v_mov_b32_e32 v107, v129
	v_mov_b32_e32 v106, v129
	v_mov_b32_e32 v97, v129
	v_mov_b32_e32 v96, v129
	v_mov_b32_e32 v95, v129
	v_mov_b32_e32 v94, v129
	v_mov_b32_e32 v93, v129
	v_mov_b32_e32 v92, v129
	v_mov_b32_e32 v91, v129
	v_mov_b32_e32 v90, v129
	v_mov_b32_e32 v81, v129
	v_mov_b32_e32 v80, v129
	v_mov_b32_e32 v79, v129
	v_mov_b32_e32 v78, v129
	v_mov_b32_e32 v77, v129
	v_mov_b32_e32 v76, v129
	v_mov_b32_e32 v75, v129
	v_mov_b32_e32 v74, v129
	v_mov_b32_e32 v121, v129
	v_mov_b32_e32 v120, v129
	v_mov_b32_e32 v119, v129
	v_mov_b32_e32 v118, v129
	v_mov_b32_e32 v117, v129
	v_mov_b32_e32 v116, v129
	v_mov_b32_e32 v115, v129
	v_mov_b32_e32 v114, v129
	v_mov_b32_e32 v105, v129
	v_mov_b32_e32 v104, v129
	v_mov_b32_e32 v103, v129
	v_mov_b32_e32 v102, v129
	v_mov_b32_e32 v101, v129
	v_mov_b32_e32 v100, v129
	v_mov_b32_e32 v99, v129
	v_mov_b32_e32 v98, v129
	v_mov_b32_e32 v89, v129
	v_mov_b32_e32 v88, v129
	v_mov_b32_e32 v87, v129
	v_mov_b32_e32 v86, v129
	v_mov_b32_e32 v85, v129
	v_mov_b32_e32 v84, v129
	v_mov_b32_e32 v83, v129
	v_mov_b32_e32 v82, v129
	v_mov_b32_e32 v73, v129
	v_mov_b32_e32 v72, v129
	v_mov_b32_e32 v71, v129
	v_mov_b32_e32 v70, v129
	v_mov_b32_e32 v69, v129
	v_mov_b32_e32 v68, v129
	v_mov_b32_e32 v67, v129
	v_mov_b32_e32 v66, v129
	v_mov_b32_e32 v65, v129
	v_mov_b32_e32 v64, v129
	v_mov_b32_e32 v63, v129
	v_mov_b32_e32 v62, v129
	v_mov_b32_e32 v61, v129
	v_mov_b32_e32 v60, v129
	v_mov_b32_e32 v59, v129
	v_mov_b32_e32 v58, v129
	v_mov_b32_e32 v53, v129
	v_mov_b32_e32 v52, v129
	v_mov_b32_e32 v51, v129
	v_mov_b32_e32 v50, v129
	v_mov_b32_e32 v45, v129
	v_mov_b32_e32 v44, v129
	v_mov_b32_e32 v43, v129
	v_mov_b32_e32 v42, v129
	v_mov_b32_e32 v37, v129
	v_mov_b32_e32 v36, v129
	v_mov_b32_e32 v35, v129
	v_mov_b32_e32 v34, v129
	v_mov_b32_e32 v29, v129
	v_mov_b32_e32 v28, v129
	v_mov_b32_e32 v27, v129
	v_mov_b32_e32 v26, v129
	v_mov_b32_e32 v17, v129
	v_mov_b32_e32 v16, v129
	v_mov_b32_e32 v15, v129
	v_mov_b32_e32 v14, v129
	v_mov_b32_e32 v13, v129
	v_mov_b32_e32 v12, v129
	v_mov_b32_e32 v11, v129
	v_mov_b32_e32 v10, v129
	v_mov_b32_e32 v57, v129
	v_mov_b32_e32 v56, v129
	v_mov_b32_e32 v55, v129
	v_mov_b32_e32 v54, v129
	v_mov_b32_e32 v49, v129
	v_mov_b32_e32 v48, v129
	v_mov_b32_e32 v47, v129
	v_mov_b32_e32 v46, v129
	v_mov_b32_e32 v41, v129
	v_mov_b32_e32 v40, v129
	v_mov_b32_e32 v39, v129
	v_mov_b32_e32 v38, v129
	v_mov_b32_e32 v33, v129
	v_mov_b32_e32 v32, v129
	v_mov_b32_e32 v31, v129
	v_mov_b32_e32 v30, v129
	v_mov_b32_e32 v25, v129
	v_mov_b32_e32 v24, v129
	v_mov_b32_e32 v23, v129
	v_mov_b32_e32 v22, v129
	v_mov_b32_e32 v21, v129
	v_mov_b32_e32 v20, v129
	v_mov_b32_e32 v19, v129
	v_mov_b32_e32 v18, v129
	v_mov_b32_e32 v9, v129
	v_mov_b32_e32 v8, v129
	v_mov_b32_e32 v7, v129
	v_mov_b32_e32 v6, v129
	v_mov_b32_e32 v5, v129
	v_mov_b32_e32 v4, v129
	v_mov_b32_e32 v3, v129
	v_mov_b32_e32 v2, v129
	s_barrier
	s_cbranch_scc1 .LBB0_218
	s_lshr_b32 s18, s17, 26
	s_add_i32 s18, s16, s18
	s_ashr_i32 s38, s18, 6
	v_lshlrev_b32_e32 v2, 4, v136
	v_lshlrev_b32_e32 v3, 6, v146
	s_movk_i32 s18, 0x3c0
	v_lshlrev_b32_e32 v4, 2, v146
	v_and_or_b32 v3, v3, s18, v2
	s_lshl_b32 s18, s20, 13
	v_and_b32_e32 v4, 32, v4
	v_bitop3_b32 v3, v3, s18, v4 bitop3:0xde
	v_lshlrev_b32_e32 v4, 2, v132
	v_lshl_or_b32 v2, v132, 6, v2
	s_lshl_b32 s18, s27, 7
	v_and_b32_e32 v4, 32, v4
	v_bitop3_b32 v137, v2, s18, v4 bitop3:0xde
	s_lshl_b64 s[18:19], s[2:3], 9
	s_or_b32 s3, s18, 0x100
	s_mul_i32 s17, s3, s17
	s_mul_hi_u32 s18, s3, s16
	s_add_i32 s17, s18, s17
	s_mul_i32 s18, s19, s16
	s_add_i32 s39, s38, -2
	s_add_i32 s17, s17, s18
	s_mul_i32 s3, s3, s16
	s_add_u32 s16, s90, s3
	s_addc_u32 s17, s91, s17
	v_mov_b32_e32 v2, 0
	v_lshl_add_u64 v[132:133], s[16:17], 0, v[0:1]
	v_lshl_add_u64 v[134:135], s[16:17], 0, v[130:131]
	s_mov_b32 s3, 0
	s_mov_b64 s[16:17], 0x80
	v_add_u32_e32 v138, 16, v3
	v_mov_b32_e32 v3, v2
	v_mov_b32_e32 v4, v2
	.p2align	6

;   DI bool next(int i, Unit& o) const { if (i != 0 || !valid) return false; o = u; return true; }
; #define PG8_STAGE(bufoff, gbase, voff) do { _Pragma("unroll") for (int _i = 0; _i < 2; ++_i) \
;     __builtin_amdgcn_global_load_lds((const unsigned*)((const char*)(gbase) + (voff)[_i]), (LAS unsigned*)(lds + (bufoff) + ldsw + _i * 8192), 16, 0, 0); } while (0)
; #define PG8_WAIT_V(n) asm volatile("s_waitcnt vmcnt(" #n ")" ::: "memory")
; #define PG8_BAR __builtin_amdgcn_s_barrier()
; template <class Epi, class Sched>
; DI void gemm_phase(LAS unsigned char* lds, const Gemm g, const Sched& S, const Epi& E) {
;     ...
;   f32x4 acc[2][2][4][2];
; #pragma unroll
;   for (int a = 0; a < 2; ++a)
; #pragma unroll
;     for (int b = 0; b < 2; ++b)
; #pragma unroll
;       for (int m = 0; m < 4; ++m)
; #pragma unroll
;         for (int n = 0; n < 2; ++n) acc[a][b][m][n] = (f32x4){0.f, 0.f, 0.f, 0.f};
;   bf16x8 At[4][2], B0[2][2], B1[2][2];
;   const char* cA = (const char*)g.A + (size_t)cur.pm * tstep; const char* cB = (const char*)g.Bt + (size_t)cur.pn * tstep;
;   PG8_STAGE(PG8_SB(0, 0), cB, voffB); PG8_STAGE(PG8_SA(0, 0), cA, voffA); PG8_STAGE(PG8_SB(0, 1), cB + hstepB, voffB); PG8_STAGE(PG8_SA(0, 1), cA + hstep, voffA);
;   if (wr == 1) PG8_BAR;
;   PG8_WAIT_V(4); PG8_BAR;
;   PG8_STAGE(PG8_SB(1, 0), cB + kstep, voffB); PG8_STAGE(PG8_SA(1, 0), cA + kstep, voffA); PG8_STAGE(PG8_SB(1, 1), cB + hstepB + kstep, voffB);
;   PG8_WAIT_V(6); PG8_BAR;
;   for (;;) {
;     const bool has_next = S.next(ui + 1, nxt);
;     const char* nA = has_next ? (const char*)g.A + (size_t)nxt.pm * tstep : cA; const char* nB = has_next ? (const char*)g.Bt + (size_t)nxt.pn * tstep : cB;
;     for (int t = 0; t < nt; t += 2) {
.LBB0_489:
	v_lshl_add_u64 v[4:5], s[2:3], 0, v[0:1]
	v_mov_b32_e32 v127, v1
	v_lshl_add_u64 v[6:7], s[2:3], 0, v[126:127]
	v_and_b32_e32 v128, 15, v2
	v_bfe_u32 v132, v2, 4, 2
	s_add_i32 m0, s18, 0x18000
	v_lshl_add_u64 v[2:3], v[4:5], 0, s[70:71]
	v_lshl_add_u64 v[8:9], s[4:5], 0, v[0:1]
	s_waitcnt vmcnt(4)
	s_barrier
	global_load_lds_dwordx4 v[2:3], off
	v_lshl_add_u64 v[2:3], v[6:7], 0, s[70:71]
	s_add_i32 m0, s18, 0x1a000
	s_add_i32 s22, s18, 0x8000
	v_lshl_add_u64 v[10:11], s[4:5], 0, v[126:127]
	global_load_lds_dwordx4 v[2:3], off
	v_lshl_add_u64 v[2:3], v[8:9], 0, s[70:71]
	s_mov_b32 m0, s22
	s_add_i32 s23, s18, 0xa000
	v_lshl_add_u64 v[12:13], s[8:9], 0, v[0:1]
	global_load_lds_dwordx4 v[2:3], off
	v_lshl_add_u64 v[2:3], v[10:11], 0, s[70:71]
	s_mov_b32 m0, s23
	v_lshl_add_u64 v[14:15], s[8:9], 0, v[126:127]
	global_load_lds_dwordx4 v[2:3], off
	s_add_i32 m0, s18, 0x1c000
	v_lshl_add_u64 v[2:3], v[12:13], 0, s[70:71]
	global_load_lds_dwordx4 v[2:3], off
	v_lshl_add_u64 v[2:3], v[14:15], 0, s[70:71]
	s_add_i32 m0, s18, 0x1e000
	s_lshl_b32 s8, s11, 5
	global_load_lds_dwordx4 v[2:3], off
	s_waitcnt vmcnt(6)
	s_and_b32 s16, s8, 0x60
	v_mov_b32_e32 v137, 0
	v_lshl_or_b32 v146, s10, 6, v128
	s_cmp_lt_i32 s6, 64
	v_mov_b32_e32 v136, v137
	v_mov_b32_e32 v135, v137
	v_mov_b32_e32 v134, v137
	v_mov_b32_e32 v125, v137
	v_mov_b32_e32 v124, v137
	v_mov_b32_e32 v123, v137
	v_mov_b32_e32 v122, v137
	v_mov_b32_e32 v113, v137
	v_mov_b32_e32 v112, v137
	v_mov_b32_e32 v111, v137
	v_mov_b32_e32 v110, v137
	v_mov_b32_e32 v109, v137
	v_mov_b32_e32 v108, v137
	v_mov_b32_e32 v107, v137
	v_mov_b32_e32 v106, v137
	v_mov_b32_e32 v97, v137
	v_mov_b32_e32 v96, v137
	v_mov_b32_e32 v95, v137
	v_mov_b32_e32 v94, v137
	v_mov_b32_e32 v93, v137
	v_mov_b32_e32 v92, v137
	v_mov_b32_e32 v91, v137
	v_mov_b32_e32 v90, v137
	v_mov_b32_e32 v81, v137
	v_mov_b32_e32 v80, v137
	v_mov_b32_e32 v79, v137
	v_mov_b32_e32 v78, v137
	v_mov_b32_e32 v77, v137
	v_mov_b32_e32 v76, v137
	v_mov_b32_e32 v75, v137
	v_mov_b32_e32 v74, v137
	v_mov_b32_e32 v121, v137
	v_mov_b32_e32 v120, v137
	v_mov_b32_e32 v119, v137
	v_mov_b32_e32 v118, v137
	v_mov_b32_e32 v117, v137
	v_mov_b32_e32 v116, v137
	v_mov_b32_e32 v115, v137
	v_mov_b32_e32 v114, v137
	v_mov_b32_e32 v105, v137
	v_mov_b32_e32 v104, v137
	v_mov_b32_e32 v103, v137
	v_mov_b32_e32 v102, v137
	v_mov_b32_e32 v101, v137
	v_mov_b32_e32 v100, v137
	v_mov_b32_e32 v99, v137
	v_mov_b32_e32 v98, v137
	v_mov_b32_e32 v89, v137
	v_mov_b32_e32 v88, v137
	v_mov_b32_e32 v87, v137
	v_mov_b32_e32 v86, v137
	v_mov_b32_e32 v85, v137
	v_mov_b32_e32 v84, v137
	v_mov_b32_e32 v83, v137
	v_mov_b32_e32 v82, v137
	v_mov_b32_e32 v73, v137
	v_mov_b32_e32 v72, v137
	v_mov_b32_e32 v71, v137
	v_mov_b32_e32 v70, v137
	v_mov_b32_e32 v69, v137
	v_mov_b32_e32 v68, v137
	v_mov_b32_e32 v67, v137
	v_mov_b32_e32 v66, v137
	v_mov_b32_e32 v65, v137
	v_mov_b32_e32 v64, v137
	v_mov_b32_e32 v63, v137
	v_mov_b32_e32 v62, v137
	v_mov_b32_e32 v61, v137
	v_mov_b32_e32 v60, v137
	v_mov_b32_e32 v59, v137
	v_mov_b32_e32 v58, v137
	v_mov_b32_e32 v53, v137
	v_mov_b32_e32 v52, v137
	v_mov_b32_e32 v51, v137
	v_mov_b32_e32 v50, v137
	v_mov_b32_e32 v45, v137
	v_mov_b32_e32 v44, v137
	v_mov_b32_e32 v43, v137
	v_mov_b32_e32 v42, v137
	v_mov_b32_e32 v37, v137
	v_mov_b32_e32 v36, v137
	v_mov_b32_e32 v35, v137
	v_mov_b32_e32 v34, v137
	v_mov_b32_e32 v29, v137
	v_mov_b32_e32 v28, v137
	v_mov_b32_e32 v27, v137
	v_mov_b32_e32 v26, v137
	v_mov_b32_e32 v21, v137
	v_mov_b32_e32 v20, v137
	v_mov_b32_e32 v19, v137
	v_mov_b32_e32 v18, v137
	v_mov_b32_e32 v13, v137
	v_mov_b32_e32 v12, v137
	v_mov_b32_e32 v11, v137
	v_mov_b32_e32 v10, v137
	v_mov_b32_e32 v57, v137
	v_mov_b32_e32 v56, v137
	v_mov_b32_e32 v55, v137
	v_mov_b32_e32 v54, v137
	v_mov_b32_e32 v49, v137
	v_mov_b32_e32 v48, v137
	v_mov_b32_e32 v47, v137
	v_mov_b32_e32 v46, v137
	v_mov_b32_e32 v41, v137
	v_mov_b32_e32 v40, v137
	v_mov_b32_e32 v39, v137
	v_mov_b32_e32 v38, v137
	v_mov_b32_e32 v33, v137
	v_mov_b32_e32 v32, v137
	v_mov_b32_e32 v31, v137
	v_mov_b32_e32 v30, v137
	v_mov_b32_e32 v25, v137
	v_mov_b32_e32 v24, v137
	v_mov_b32_e32 v23, v137
	v_mov_b32_e32 v22, v137
	v_mov_b32_e32 v17, v137
	v_mov_b32_e32 v16, v137
	v_mov_b32_e32 v15, v137
	v_mov_b32_e32 v14, v137
	v_mov_b32_e32 v9, v137
	v_mov_b32_e32 v8, v137
	v_mov_b32_e32 v7, v137
	v_mov_b32_e32 v6, v137
	v_mov_b32_e32 v5, v137
	v_mov_b32_e32 v4, v137
	v_mov_b32_e32 v3, v137
	v_mov_b32_e32 v2, v137
	s_barrier
	s_cbranch_scc1 .LBB0_493
	s_lshr_b32 s7, s7, 26
	s_add_i32 s7, s6, s7
	s_ashr_i32 s24, s7, 6
	v_lshlrev_b32_e32 v2, 4, v132
	v_lshlrev_b32_e32 v3, 6, v146
	s_movk_i32 s7, 0x3c0
	v_lshlrev_b32_e32 v4, 2, v146
	v_and_or_b32 v3, v3, s7, v2
	s_lshl_b32 s7, s10, 13
	v_and_b32_e32 v4, 32, v4
	v_bitop3_b32 v3, v3, s7, v4 bitop3:0xde
	v_lshlrev_b32_e32 v4, 2, v128
	v_lshl_or_b32 v2, v128, 6, v2
	s_lshl_b32 s7, s16, 7
	v_and_b32_e32 v4, 32, v4
	v_bitop3_b32 v133, v2, s7, v4 bitop3:0xde
	s_lshl_b32 s7, s13, 9
	s_bitset1_b32 s7, 8
	s_add_i32 s25, s24, -2
	s_mul_hi_i32 s8, s7, s6
	s_mul_i32 s7, s7, s6
	s_add_u32 s6, s90, s7
	s_addc_u32 s7, s91, s8
	v_mov_b32_e32 v2, 0
	v_lshl_add_u64 v[128:129], s[6:7], 0, v[0:1]
	v_lshl_add_u64 v[130:131], s[6:7], 0, v[126:127]
	s_mov_b32 s8, 0
	s_mov_b64 s[6:7], 0x2000080
	v_add_u32_e32 v138, 16, v3
	v_mov_b32_e32 v3, v2
	v_mov_b32_e32 v4, v2
	s_waitcnt vmcnt(0)
	.p2align	6

; template <class Epi, class Sched>
; DI void gemm_phase(LAS unsigned char* lds, const Gemm g, const Sched& S, const Epi& E) {
;     ...
;     if (!has_next) break;
; #pragma unroll
;     for (int a = 0; a < 2; ++a)
; #pragma unroll
;       for (int b = 0; b < 2; ++b)
; #pragma unroll
;         for (int m = 0; m < 4; ++m)
; #pragma unroll
;           for (int n = 0; n < 2; ++n) acc[a][b][m][n] = (f32x4){0.f, 0.f, 0.f, 0.f};
;     cur = nxt; cA = nA; cB = nB; ++ui;
.LBB0_517:
	v_mov_b32_e32 v177, 0
	s_andn2_b64 vcc, exec, s[18:19]
	v_mov_b32_e32 v176, v177
	v_mov_b32_e32 v175, v177
	v_mov_b32_e32 v174, v177
	v_mov_b32_e32 v173, v177
	v_mov_b32_e32 v172, v177
	v_mov_b32_e32 v171, v177
	v_mov_b32_e32 v170, v177
	s_waitcnt vmcnt(0)
	v_mov_b32_e32 v161, v177
	v_mov_b32_e32 v160, v177
	v_mov_b32_e32 v159, v177
	v_mov_b32_e32 v158, v177
	v_mov_b32_e32 v157, v177
	v_mov_b32_e32 v156, v177
	v_mov_b32_e32 v155, v177
	v_mov_b32_e32 v154, v177
	v_mov_b32_e32 v145, v177
	v_mov_b32_e32 v144, v177
	v_mov_b32_e32 v143, v177
	v_mov_b32_e32 v142, v177
	v_mov_b32_e32 v141, v177
	v_mov_b32_e32 v140, v177
	v_mov_b32_e32 v139, v177
	v_mov_b32_e32 v138, v177
	v_mov_b32_e32 v113, v177
	v_mov_b32_e32 v112, v177
	v_mov_b32_e32 v111, v177
	v_mov_b32_e32 v110, v177
	v_mov_b32_e32 v109, v177
	v_mov_b32_e32 v108, v177
	v_mov_b32_e32 v107, v177
	v_mov_b32_e32 v106, v177
	v_mov_b32_e32 v169, v177
	v_mov_b32_e32 v168, v177
	v_mov_b32_e32 v167, v177
	v_mov_b32_e32 v166, v177
	v_mov_b32_e32 v165, v177
	v_mov_b32_e32 v164, v177
	v_mov_b32_e32 v163, v177
	v_mov_b32_e32 v162, v177
	v_mov_b32_e32 v153, v177
	v_mov_b32_e32 v152, v177
	v_mov_b32_e32 v151, v177
	v_mov_b32_e32 v150, v177
	v_mov_b32_e32 v149, v177
	v_mov_b32_e32 v148, v177
	v_mov_b32_e32 v147, v177
	v_mov_b32_e32 v146, v177
	v_mov_b32_e32 v137, v177
	v_mov_b32_e32 v136, v177
	v_mov_b32_e32 v135, v177
	v_mov_b32_e32 v134, v177
	v_mov_b32_e32 v133, v177
	v_mov_b32_e32 v132, v177
	v_mov_b32_e32 v131, v177
	v_mov_b32_e32 v130, v177
	v_mov_b32_e32 v105, v177
	v_mov_b32_e32 v104, v177
	v_mov_b32_e32 v103, v177
	v_mov_b32_e32 v102, v177
	v_mov_b32_e32 v93, v177
	v_mov_b32_e32 v92, v177
	v_mov_b32_e32 v91, v177
	v_mov_b32_e32 v90, v177
	v_mov_b32_e32 v65, v177
	v_mov_b32_e32 v64, v177
	v_mov_b32_e32 v63, v177
	v_mov_b32_e32 v62, v177
	v_mov_b32_e32 v61, v177
	v_mov_b32_e32 v60, v177
	v_mov_b32_e32 v59, v177
	v_mov_b32_e32 v58, v177
	v_mov_b32_e32 v49, v177
	v_mov_b32_e32 v48, v177
	v_mov_b32_e32 v47, v177
	v_mov_b32_e32 v46, v177
	v_mov_b32_e32 v45, v177
	v_mov_b32_e32 v44, v177
	v_mov_b32_e32 v43, v177
	v_mov_b32_e32 v42, v177
	v_mov_b32_e32 v33, v177
	v_mov_b32_e32 v32, v177
	v_mov_b32_e32 v31, v177
	v_mov_b32_e32 v30, v177
	v_mov_b32_e32 v29, v177
	v_mov_b32_e32 v28, v177
	v_mov_b32_e32 v27, v177
	v_mov_b32_e32 v26, v177
	v_mov_b32_e32 v17, v177
	v_mov_b32_e32 v16, v177
	v_mov_b32_e32 v15, v177
	v_mov_b32_e32 v14, v177
	v_mov_b32_e32 v13, v177
	v_mov_b32_e32 v12, v177
	v_mov_b32_e32 v11, v177
	v_mov_b32_e32 v10, v177
	v_mov_b32_e32 v57, v177
	v_mov_b32_e32 v56, v177
	v_mov_b32_e32 v55, v177
	v_mov_b32_e32 v54, v177
	v_mov_b32_e32 v53, v177
	v_mov_b32_e32 v52, v177
	v_mov_b32_e32 v51, v177
	v_mov_b32_e32 v50, v177
	v_mov_b32_e32 v41, v177
	v_mov_b32_e32 v40, v177
	v_mov_b32_e32 v39, v177
	v_mov_b32_e32 v38, v177
	v_mov_b32_e32 v37, v177
	v_mov_b32_e32 v36, v177
	v_mov_b32_e32 v35, v177
	v_mov_b32_e32 v34, v177
	v_mov_b32_e32 v25, v177
	v_mov_b32_e32 v24, v177
	v_mov_b32_e32 v23, v177
	v_mov_b32_e32 v22, v177
	v_mov_b32_e32 v21, v177
	v_mov_b32_e32 v20, v177
	v_mov_b32_e32 v19, v177
	v_mov_b32_e32 v18, v177
	v_mov_b32_e32 v9, v177
	v_mov_b32_e32 v8, v177
	v_mov_b32_e32 v7, v177
	v_mov_b32_e32 v6, v177
	v_mov_b32_e32 v5, v177
	v_mov_b32_e32 v4, v177
	v_mov_b32_e32 v3, v177
	v_mov_b32_e32 v2, v177
	s_cbranch_vccnz .LBB0_521
	s_add_u32 s2, s2, 0x80
	s_addc_u32 s3, s3, 0
	s_add_u32 s11, s8, 0x100
	v_mov_b32_e32 v200, v184
	v_mov_b32_e32 v201, 0x358637bd
	v_mov_b32_e32 v210, 0x3e38aa3b
	v_mov_b32_e32 v217, 1
	v_mov_b64_e32 v[178:179], 0x200
	s_addc_u32 s22, s9, 0
	s_mov_b32 s6, 0
	.p2align	6

;   DI bool next(int i, Unit& o) const { if (i != 0 || !valid) return false; o = u; return true; }
; #define PG8_STAGE(bufoff, gbase, voff) do { _Pragma("unroll") for (int _i = 0; _i < 2; ++_i) \
;     __builtin_amdgcn_global_load_lds((const unsigned*)((const char*)(gbase) + (voff)[_i]), (LAS unsigned*)(lds + (bufoff) + ldsw + _i * 8192), 16, 0, 0); } while (0)
; #define PG8_WAIT_V(n) asm volatile("s_waitcnt vmcnt(" #n ")" ::: "memory")
; #define PG8_BAR __builtin_amdgcn_s_barrier()
; template <class Epi, class Sched>
; DI void gemm_phase(LAS unsigned char* lds, const Gemm g, const Sched& S, const Epi& E) {
;     ...
;   f32x4 acc[2][2][4][2];
; #pragma unroll
;   for (int a = 0; a < 2; ++a)
; #pragma unroll
;     for (int b = 0; b < 2; ++b)
; #pragma unroll
;       for (int m = 0; m < 4; ++m)
; #pragma unroll
;         for (int n = 0; n < 2; ++n) acc[a][b][m][n] = (f32x4){0.f, 0.f, 0.f, 0.f};
;   bf16x8 At[4][2], B0[2][2], B1[2][2];
;   const char* cA = (const char*)g.A + (size_t)cur.pm * tstep; const char* cB = (const char*)g.Bt + (size_t)cur.pn * tstep;
;   PG8_STAGE(PG8_SB(0, 0), cB, voffB); PG8_STAGE(PG8_SA(0, 0), cA, voffA); PG8_STAGE(PG8_SB(0, 1), cB + hstepB, voffB); PG8_STAGE(PG8_SA(0, 1), cA + hstep, voffA);
;   if (wr == 1) PG8_BAR;
;   PG8_WAIT_V(4); PG8_BAR;
;   PG8_STAGE(PG8_SB(1, 0), cB + kstep, voffB); PG8_STAGE(PG8_SA(1, 0), cA + kstep, voffA); PG8_STAGE(PG8_SB(1, 1), cB + hstepB + kstep, voffB);
;   PG8_WAIT_V(6); PG8_BAR;
;   for (;;) {
;     const bool has_next = S.next(ui + 1, nxt);
;     const char* nA = has_next ? (const char*)g.A + (size_t)nxt.pm * tstep : cA; const char* nB = has_next ? (const char*)g.Bt + (size_t)nxt.pn * tstep : cB;
;     for (int t = 0; t < nt; t += 2) {
.LBB0_829:
	v_lshl_add_u64 v[4:5], s[4:5], 0, v[0:1]
	v_mov_b32_e32 v83, v1
	v_lshl_add_u64 v[6:7], s[4:5], 0, v[82:83]
	v_mov_b32_e32 v87, v1
	v_and_b32_e32 v150, 15, v2
	v_bfe_u32 v148, v2, 4, 2
	s_add_i32 m0, s18, 0x18000
	v_lshl_add_u64 v[2:3], v[4:5], 0, s[70:71]
	v_lshl_add_u64 v[8:9], s[6:7], 0, v[86:87]
	v_mov_b32_e32 v85, v1
	s_waitcnt vmcnt(4)
	s_barrier
	global_load_lds_dwordx4 v[2:3], off
	v_lshl_add_u64 v[2:3], v[6:7], 0, s[70:71]
	s_add_i32 m0, s18, 0x1a000
	s_add_i32 s22, s18, 0x8000
	v_lshl_add_u64 v[10:11], s[6:7], 0, v[84:85]
	global_load_lds_dwordx4 v[2:3], off
	v_lshl_add_u64 v[2:3], v[8:9], 0, s[70:71]
	s_mov_b32 m0, s22
	s_add_i32 s23, s18, 0xa000
	v_lshl_add_u64 v[12:13], s[10:11], 0, v[0:1]
	global_load_lds_dwordx4 v[2:3], off
	v_lshl_add_u64 v[2:3], v[10:11], 0, s[70:71]
	s_mov_b32 m0, s23
	v_lshl_add_u64 v[14:15], s[10:11], 0, v[82:83]
	global_load_lds_dwordx4 v[2:3], off
	s_add_i32 m0, s18, 0x1c000
	v_lshl_add_u64 v[2:3], v[12:13], 0, s[70:71]
	global_load_lds_dwordx4 v[2:3], off
	v_lshl_add_u64 v[2:3], v[14:15], 0, s[70:71]
	s_add_i32 m0, s18, 0x1e000
	s_and_b32 s16, s13, 3
	global_load_lds_dwordx4 v[2:3], off
	s_waitcnt vmcnt(6)
	s_lshl_b32 s15, s12, 6
	v_mov_b32_e32 v145, 0
	s_cmp_lt_i32 s8, 64
	v_mov_b32_e32 v144, v145
	v_mov_b32_e32 v143, v145
	v_mov_b32_e32 v142, v145
	v_mov_b32_e32 v141, v145
	v_mov_b32_e32 v140, v145
	v_mov_b32_e32 v139, v145
	v_mov_b32_e32 v138, v145
	v_mov_b32_e32 v129, v145
	v_mov_b32_e32 v128, v145
	v_mov_b32_e32 v127, v145
	v_mov_b32_e32 v126, v145
	v_mov_b32_e32 v125, v145
	v_mov_b32_e32 v124, v145
	v_mov_b32_e32 v123, v145
	v_mov_b32_e32 v122, v145
	v_mov_b32_e32 v113, v145
	v_mov_b32_e32 v112, v145
	v_mov_b32_e32 v111, v145
	v_mov_b32_e32 v110, v145
	v_mov_b32_e32 v109, v145
	v_mov_b32_e32 v108, v145
	v_mov_b32_e32 v107, v145
	v_mov_b32_e32 v106, v145
	v_mov_b32_e32 v81, v145
	v_mov_b32_e32 v80, v145
	v_mov_b32_e32 v79, v145
	v_mov_b32_e32 v78, v145
	v_mov_b32_e32 v77, v145
	v_mov_b32_e32 v76, v145
	v_mov_b32_e32 v75, v145
	v_mov_b32_e32 v74, v145
	v_mov_b32_e32 v137, v145
	v_mov_b32_e32 v136, v145
	v_mov_b32_e32 v135, v145
	v_mov_b32_e32 v134, v145
	v_mov_b32_e32 v133, v145
	v_mov_b32_e32 v132, v145
	v_mov_b32_e32 v131, v145
	v_mov_b32_e32 v130, v145
	v_mov_b32_e32 v121, v145
	v_mov_b32_e32 v120, v145
	v_mov_b32_e32 v119, v145
	v_mov_b32_e32 v118, v145
	v_mov_b32_e32 v117, v145
	v_mov_b32_e32 v116, v145
	v_mov_b32_e32 v115, v145
	v_mov_b32_e32 v114, v145
	v_mov_b32_e32 v105, v145
	v_mov_b32_e32 v104, v145
	v_mov_b32_e32 v103, v145
	v_mov_b32_e32 v102, v145
	v_mov_b32_e32 v101, v145
	v_mov_b32_e32 v100, v145
	v_mov_b32_e32 v99, v145
	v_mov_b32_e32 v98, v145
	v_mov_b32_e32 v73, v145
	v_mov_b32_e32 v72, v145
	v_mov_b32_e32 v71, v145
	v_mov_b32_e32 v70, v145
	v_mov_b32_e32 v69, v145
	v_mov_b32_e32 v68, v145
	v_mov_b32_e32 v67, v145
	v_mov_b32_e32 v66, v145
	v_mov_b32_e32 v65, v145
	v_mov_b32_e32 v64, v145
	v_mov_b32_e32 v63, v145
	v_mov_b32_e32 v62, v145
	v_mov_b32_e32 v61, v145
	v_mov_b32_e32 v60, v145
	v_mov_b32_e32 v59, v145
	v_mov_b32_e32 v58, v145
	v_mov_b32_e32 v49, v145
	v_mov_b32_e32 v48, v145
	v_mov_b32_e32 v47, v145
	v_mov_b32_e32 v46, v145
	v_mov_b32_e32 v45, v145
	v_mov_b32_e32 v44, v145
	v_mov_b32_e32 v43, v145
	v_mov_b32_e32 v42, v145
	v_mov_b32_e32 v33, v145
	v_mov_b32_e32 v32, v145
	v_mov_b32_e32 v31, v145
	v_mov_b32_e32 v30, v145
	v_mov_b32_e32 v29, v145
	v_mov_b32_e32 v28, v145
	v_mov_b32_e32 v27, v145
	v_mov_b32_e32 v26, v145
	v_mov_b32_e32 v17, v145
	v_mov_b32_e32 v16, v145
	v_mov_b32_e32 v15, v145
	v_mov_b32_e32 v14, v145
	v_mov_b32_e32 v13, v145
	v_mov_b32_e32 v12, v145
	v_mov_b32_e32 v11, v145
	v_mov_b32_e32 v10, v145
	v_mov_b32_e32 v57, v145
	v_mov_b32_e32 v56, v145
	v_mov_b32_e32 v55, v145
	v_mov_b32_e32 v54, v145
	v_mov_b32_e32 v53, v145
	v_mov_b32_e32 v52, v145
	v_mov_b32_e32 v51, v145
	v_mov_b32_e32 v50, v145
	v_mov_b32_e32 v41, v145
	v_mov_b32_e32 v40, v145
	v_mov_b32_e32 v39, v145
	v_mov_b32_e32 v38, v145
	v_mov_b32_e32 v37, v145
	v_mov_b32_e32 v36, v145
	v_mov_b32_e32 v35, v145
	v_mov_b32_e32 v34, v145
	v_mov_b32_e32 v25, v145
	v_mov_b32_e32 v24, v145
	v_mov_b32_e32 v23, v145
	v_mov_b32_e32 v22, v145
	v_mov_b32_e32 v21, v145
	v_mov_b32_e32 v20, v145
	v_mov_b32_e32 v19, v145
	v_mov_b32_e32 v18, v145
	v_mov_b32_e32 v9, v145
	v_mov_b32_e32 v8, v145
	v_mov_b32_e32 v7, v145
	v_mov_b32_e32 v6, v145
	v_mov_b32_e32 v5, v145
	v_mov_b32_e32 v4, v145
	v_mov_b32_e32 v3, v145
	v_mov_b32_e32 v2, v145
	s_barrier
	s_cbranch_scc1 .LBB0_832
	s_lshr_b32 s9, s9, 26
	s_add_i32 s9, s8, s9
	v_or_b32_e32 v2, s15, v150
	s_ashr_i32 s24, s9, 6
	v_lshlrev_b32_e32 v3, 6, v2
	v_lshlrev_b32_e32 v4, 4, v148
	s_movk_i32 s9, 0x3c0
	v_lshlrev_b32_e32 v2, 2, v2
	v_and_or_b32 v3, v3, s9, v4
	s_lshl_b32 s9, s12, 13
	v_and_b32_e32 v2, 32, v2
	v_bitop3_b32 v5, v3, s9, v2 bitop3:0xde
	v_lshlrev_b32_e32 v3, 2, v150
	v_lshl_or_b32 v2, v150, 6, v4
	s_lshl_b32 s9, s16, 12
	v_and_b32_e32 v3, 32, v3
	v_readlane_b32 s10, v253, 35
	s_add_i32 s25, s24, -2
	v_bitop3_b32 v92, v2, s9, v3 bitop3:0xde
	s_mul_hi_i32 s9, s10, s8
	s_mul_i32 s8, s10, s8
	v_add_u32_e32 v2, v94, v88
	s_add_u32 s8, s86, s8
	v_add_lshl_u32 v2, v2, v89, 1
	v_mov_b32_e32 v3, v1
	s_addc_u32 s9, s87, s9
	v_lshl_add_u64 v[88:89], s[8:9], 0, v[2:3]
	v_add_u32_e32 v2, v93, v90
	v_add_lshl_u32 v2, v2, v91, 1
	v_lshl_add_u64 v[90:91], s[8:9], 0, v[2:3]
	v_mov_b32_e32 v2, 0
	s_mov_b32 s10, 0
	s_mov_b64 s[8:9], 0x2000080
	v_add_u32_e32 v93, 16, v5
	v_mov_b32_e32 v3, v2
	v_mov_b32_e32 v4, v2
	v_mov_b32_e32 v5, v2
	.p2align	6
